# attention loops: cross-half row-max exchange via v_permlane32_swap instead of ds_bpermute
# speedup vs baseline: 1.0129x; 1.0044x over previous
; #define MFMA32(a, b, c) __builtin_amdgcn_mfma_f32_32x32x16_bf16((a), (b), (c), 0, 0, 0)
; DI int crow(int reg, int h) { return (reg & 3) + 8 * (reg >> 2) + 4 * h; }
; template <int MODE>
; DI void attn_mfma(const Params& p, int l, int b, int hd, int qb, unsigned char* smem) {
;     ...
; #pragma unroll
;     for (int ks = 0; ks < KS; ++ks) {
;       const int kk = mp * 2 + ks;
;       const int key0 = r, key1 = 32 + r;
;       const int o0 = key0 * 128 + (((2 * kk + h2) ^ ((key0 >> 1) & 7)) << 4), o1 = key1 * 128 + (((2 * kk + h2) ^ ((key1 >> 1) & 7)) << 4);
;       SA0 = MFMA32(*(const bf16x8*)(sK + o0), qf[ks], SA0);
;       SA1 = MFMA32(*(const bf16x8*)(sK + o1), qf[ks], SA1);
;       SB0 = MFMA32(*(const bf16x8*)(sK + 16896 + o0), qf[ks], SB0);
;       SB1 = MFMA32(*(const bf16x8*)(sK + 16896 + o1), qf[ks], SB1);
;     }
; #pragma unroll
;     for (int hf = 0; hf < 2; ++hf) {
;     const unsigned char* sVc = sV + hf * 16896;
;     const int tbcur = tile_base(j + hf);
;     f32x16 S[2];
;     S[0] = hf == 0 ? SA0 : SB0;
;     S[1] = hf == 0 ? SA1 : SB1;
;     if (MODE == 1 && j + hf >= 4) {
;       const int iq = tq - NCTX;
;       const int jb = tbcur - NCTX;
; #pragma unroll
;       for (int mt = 0; mt < 2; ++mt)
; #pragma unroll
;         for (int i = 0; i < 16; ++i) {
;           const int dd = iq - (jb + mt * 32 + crow(i, h2));
;           if (dd > 128 || dd < -128) S[mt][i] = -1e30f;
;         }
;     }
;     float mx = -1e30f;
; #pragma unroll
;     for (int mt = 0; mt < 2; ++mt)
; #pragma unroll
;       for (int i = 0; i < 16; ++i) mx = fmaxf(mx, S[mt][i]);
;     mx = fmaxf(mx, __shfl_xor(mx, 32));
;     const float zmx = mx * cexp;
;     if (__any(zmx > mrun + 8.f)) {
;       const float mnew = fmaxf(mrun, zmx);
;       const float alpha = __builtin_amdgcn_exp2f(mrun - mnew);
;       mrun = mnew;
;       lsum *= alpha;
;       const f32x2 al2 = {alpha, alpha};
; #pragma unroll
;       for (int vt = 0; vt < 2; ++vt)
; #pragma unroll
;         for (int i = 0; i < 8; ++i) {
;           f32x2 o = {O[vt][2 * i], O[vt][2 * i + 1]};
;           o = o * al2;
;           O[vt][2 * i] = o.x; O[vt][2 * i + 1] = o.y;
;         }
;     }
.LBB0_582:
	s_mov_b32 s5, 0xf149f2ca
	s_mov_b32 s8, 0x3e8293ee
	s_waitcnt lgkmcnt(6)
	v_mfma_f32_32x32x16_bf16 v[80:95], v[204:207], v[96:99], 0
	v_mfma_f32_32x32x16_bf16 v[80:95], v[208:211], v[100:103], v[80:95]
	s_waitcnt lgkmcnt(4)
	v_mfma_f32_32x32x16_bf16 v[64:79], v[212:215], v[96:99], 0
	v_mfma_f32_32x32x16_bf16 v[64:79], v[216:219], v[100:103], v[64:79]
	s_waitcnt lgkmcnt(0)
	v_mfma_f32_32x32x16_bf16 v[48:63], v[220:223], v[96:99], 0
	ds_read2_b64 v[204:207], v236 offset1:2
	ds_read2_b64 v[208:211], v237 offset0:32 offset1:34
	ds_read2_b64 v[212:215], v236 offset0:4 offset1:6
	ds_read2_b64 v[216:219], v237 offset0:36 offset1:38
	v_mfma_f32_32x32x16_bf16 v[48:63], v[224:227], v[100:103], v[48:63]
	s_nop 1
	v_max3_f32 v146, v80, s5, v81
	v_max3_f32 v146, v146, v82, v83
	v_max3_f32 v146, v146, v84, v85
	v_max3_f32 v146, v146, v86, v87
	v_max3_f32 v146, v146, v88, v89
	v_max3_f32 v146, v146, v90, v91
	v_max3_f32 v146, v146, v92, v93
	v_max3_f32 v146, v146, v94, v95
	v_mfma_f32_32x32x16_bf16 v[32:47], v[228:231], v[96:99], 0
	v_max3_f32 v146, v146, v64, v65
	v_max3_f32 v146, v146, v66, v67
	v_max3_f32 v146, v146, v68, v69
	v_max3_f32 v146, v146, v70, v71
	v_mfma_f32_32x32x16_bf16 v[32:47], v[232:235], v[100:103], v[32:47]
	v_max3_f32 v146, v146, v72, v73
	v_max3_f32 v146, v146, v74, v75
	v_max3_f32 v146, v146, v76, v77
	v_max3_f32 v146, v146, v78, v79
	v_mov_b32_e32 v147, v146
	s_nop 1
	v_permlane32_swap_b32_e32 v147, v146
	ds_read2_b64 v[220:223], v236 offset0:8 offset1:10
	ds_read2_b64 v[224:227], v237 offset0:40 offset1:42
	ds_read2_b64 v[228:231], v236 offset0:12 offset1:14
	ds_read2_b64 v[232:235], v237 offset0:44 offset1:46
	s_waitcnt lgkmcnt(4)
	v_max_f32_e32 v147, v147, v147
	v_max_f32_e32 v146, v146, v147
	v_mul_f32_e32 v147, 0x3e8293ee, v146
	v_add_f32_e32 v146, 0x41000000, v140
	v_cmp_gt_f32_e32 vcc, v147, v146
	s_cbranch_vccz .Laa_nra
	v_max_f32_e32 v146, v147, v147
	v_max_f32_e32 v147, v140, v140
	v_max_f32_e32 v147, v147, v146
	v_sub_f32_e32 v140, v140, v147
	v_exp_f32_e32 v140, v140
	v_add_f32_e32 v146, 0x41000000, v147
	v_pk_mul_f32 v[18:19], v[18:19], v[140:141] op_sel_hi:[1,0]
	v_pk_mul_f32 v[20:21], v[20:21], v[140:141] op_sel_hi:[1,0]
	v_pk_mul_f32 v[22:23], v[22:23], v[140:141] op_sel_hi:[1,0]
	v_pk_mul_f32 v[24:25], v[24:25], v[140:141] op_sel_hi:[1,0]
	v_pk_mul_f32 v[26:27], v[26:27], v[140:141] op_sel_hi:[1,0]
	v_pk_mul_f32 v[28:29], v[28:29], v[140:141] op_sel_hi:[1,0]
	v_pk_mul_f32 v[16:17], v[16:17], v[140:141] op_sel_hi:[1,0]
	v_pk_mul_f32 v[30:31], v[30:31], v[140:141] op_sel_hi:[1,0]
	v_pk_mul_f32 v[0:1], v[0:1], v[140:141] op_sel_hi:[1,0]
	v_pk_mul_f32 v[2:3], v[2:3], v[140:141] op_sel_hi:[1,0]
	v_pk_mul_f32 v[4:5], v[4:5], v[140:141] op_sel_hi:[1,0]
	v_pk_mul_f32 v[6:7], v[6:7], v[140:141] op_sel_hi:[1,0]
	v_pk_mul_f32 v[8:9], v[8:9], v[140:141] op_sel_hi:[1,0]
	v_pk_mul_f32 v[10:11], v[10:11], v[140:141] op_sel_hi:[1,0]
	v_pk_mul_f32 v[12:13], v[12:13], v[140:141] op_sel_hi:[1,0]
	v_pk_mul_f32 v[14:15], v[14:15], v[140:141] op_sel_hi:[1,0]
	v_mul_f32_e32 v200, v200, v140
	v_mov_b32_e32 v140, v147
; DI unsigned pk2(float a, float b) { hwf32x2 f = {a, b}; hwbf16x2 r = __builtin_convertvector(f, hwbf16x2); return __builtin_bit_cast(unsigned, r); }
; #define MFMA32(a, b, c) __builtin_amdgcn_mfma_f32_32x32x16_bf16((a), (b), (c), 0, 0, 0)
; template <int MODE>
; DI void attn_mfma(const Params& p, int l, int b, int hd, int qb, unsigned char* smem) {
;     ...
;     float mx = -1e30f;
; #pragma unroll
;     for (int mt = 0; mt < 2; ++mt)
; #pragma unroll
;       for (int i = 0; i < 16; ++i) mx = fmaxf(mx, S[mt][i]);
;     mx = fmaxf(mx, __shfl_xor(mx, 32));
;     const float zmx = mx * cexp;
;     if (__any(zmx > mrun + 8.f)) {
;       const float mnew = fmaxf(mrun, zmx);
;       const float alpha = __builtin_amdgcn_exp2f(mrun - mnew);
;       mrun = mnew;
;       lsum *= alpha;
;       const f32x2 al2 = {alpha, alpha};
; #pragma unroll
;       for (int vt = 0; vt < 2; ++vt)
; #pragma unroll
;         for (int i = 0; i < 8; ++i) {
;           f32x2 o = {O[vt][2 * i], O[vt][2 * i + 1]};
;           o = o * al2;
;           O[vt][2 * i] = o.x; O[vt][2 * i + 1] = o.y;
;         }
;     }
;     const f32x2 c2 = {cexp, cexp}, m2 = {mrun, mrun};
;     f32x2 ps2 = {0.f, 0.f};
;     unsigned pk[2][8];
; #pragma unroll
;     for (int mt = 0; mt < 2; ++mt)
; #pragma unroll
;       for (int i = 0; i < 8; ++i) {
;         f32x2 z = {S[mt][2 * i], S[mt][2 * i + 1]};
;         z = z * c2 - m2;
;         f32x2 pv = {__builtin_amdgcn_exp2f(z.x), __builtin_amdgcn_exp2f(z.y)};
;         ps2 = ps2 + pv;
;         pk[mt][i] = pk2(pv.x, pv.y);
;       }
;     lsum += ps2.x + ps2.y;
; #pragma unroll
;     for (int mt = 0; mt < 2; ++mt)
; #pragma unroll
;       for (int s = 0; s < 2; ++s) {
;         const uint4 pu = make_uint4(pk[mt][4 * s], pk[mt][4 * s + 1], pk[mt][4 * s + 2], pk[mt][4 * s + 3]);
;         const bf16x8 pf = __builtin_bit_cast(bf16x8, pu);
; #pragma unroll
;         for (int vt = 0; vt < 2; ++vt) {
;           const unsigned char* bp = sVc + (vt * 32 + r) * 136 + (mt * 32 + 16 * s + 4 * h2) * 2;
;           const uint2 lo = *(const uint2*)(bp);
;           const uint2 hi = *(const uint2*)(bp + 16);
;           const uint4 u = make_uint4(lo.x, lo.y, hi.x, hi.y);
;           O[vt] = MFMA32(__builtin_bit_cast(bf16x8, u), pf, O[vt]);
;         }
;       }
.Laa_nra:
	v_fma_f32 v80, v80, s8, -v140
	v_fma_f32 v81, v81, s8, -v140
	v_fma_f32 v82, v82, s8, -v140
	v_fma_f32 v83, v83, s8, -v140
	v_fma_f32 v84, v84, s8, -v140
	v_fma_f32 v85, v85, s8, -v140
	v_fma_f32 v86, v86, s8, -v140
	v_fma_f32 v87, v87, s8, -v140
	v_exp_f32_e32 v80, v80
	v_exp_f32_e32 v81, v81
	v_exp_f32_e32 v82, v82
	v_exp_f32_e32 v83, v83
	v_exp_f32_e32 v84, v84
	v_exp_f32_e32 v85, v85
	v_exp_f32_e32 v86, v86
	v_exp_f32_e32 v87, v87
	v_add_f32_e64 v148, v80, 0
	v_add_f32_e64 v149, v81, 0
	v_add_f32_e32 v148, v82, v148
	v_add_f32_e32 v149, v83, v149
	v_add_f32_e32 v148, v84, v148
	v_add_f32_e32 v149, v85, v149
	v_add_f32_e32 v148, v86, v148
	v_add_f32_e32 v149, v87, v149
	v_cvt_pk_bf16_f32 v80, v80, v81
	v_cvt_pk_bf16_f32 v81, v82, v83
	v_cvt_pk_bf16_f32 v82, v84, v85
	v_cvt_pk_bf16_f32 v83, v86, v87
	v_fma_f32 v88, v88, s8, -v140
	v_fma_f32 v89, v89, s8, -v140
	v_fma_f32 v90, v90, s8, -v140
	v_mfma_f32_32x32x16_bf16 v[16:31], v[204:207], v[80:83], v[16:31]
	v_fma_f32 v91, v91, s8, -v140
	v_fma_f32 v92, v92, s8, -v140
	v_fma_f32 v93, v93, s8, -v140
	v_fma_f32 v94, v94, s8, -v140
	v_fma_f32 v95, v95, s8, -v140
	v_exp_f32_e32 v88, v88
	v_exp_f32_e32 v89, v89
	v_exp_f32_e32 v90, v90
	v_exp_f32_e32 v91, v91
	v_exp_f32_e32 v92, v92
	v_exp_f32_e32 v93, v93
	v_exp_f32_e32 v94, v94
	v_mfma_f32_32x32x16_bf16 v[0:15], v[208:211], v[80:83], v[0:15]
	v_exp_f32_e32 v95, v95
	v_add_f32_e32 v148, v88, v148
	v_add_f32_e32 v149, v89, v149
	v_add_f32_e32 v148, v90, v148
	v_add_f32_e32 v149, v91, v149
	v_add_f32_e32 v148, v92, v148
	v_add_f32_e32 v149, v93, v149
	v_add_f32_e32 v148, v94, v148
	v_add_f32_e32 v149, v95, v149
	v_cvt_pk_bf16_f32 v88, v88, v89
	v_cvt_pk_bf16_f32 v89, v90, v91
	v_cvt_pk_bf16_f32 v90, v92, v93
	v_cvt_pk_bf16_f32 v91, v94, v95
	v_fma_f32 v64, v64, s8, -v140
	v_fma_f32 v65, v65, s8, -v140
	v_fma_f32 v66, v66, s8, -v140
	v_mfma_f32_32x32x16_bf16 v[16:31], v[212:215], v[88:91], v[16:31]
	v_fma_f32 v67, v67, s8, -v140
	v_fma_f32 v68, v68, s8, -v140
	v_fma_f32 v69, v69, s8, -v140
	v_fma_f32 v70, v70, s8, -v140
	v_fma_f32 v71, v71, s8, -v140
	v_exp_f32_e32 v64, v64
	v_exp_f32_e32 v65, v65
	v_exp_f32_e32 v66, v66
	v_exp_f32_e32 v67, v67
	v_exp_f32_e32 v68, v68
	v_exp_f32_e32 v69, v69
	v_exp_f32_e32 v70, v70
	v_mfma_f32_32x32x16_bf16 v[0:15], v[216:219], v[88:91], v[0:15]
	v_exp_f32_e32 v71, v71
	v_add_f32_e32 v148, v64, v148
	v_add_f32_e32 v149, v65, v149
	v_add_f32_e32 v148, v66, v148
	v_add_f32_e32 v149, v67, v149
	v_add_f32_e32 v148, v68, v148
	v_add_f32_e32 v149, v69, v149
	v_add_f32_e32 v148, v70, v148
	v_add_f32_e32 v149, v71, v149
	v_cvt_pk_bf16_f32 v84, v64, v65
	v_cvt_pk_bf16_f32 v85, v66, v67
	v_cvt_pk_bf16_f32 v86, v68, v69
	v_cvt_pk_bf16_f32 v87, v70, v71
	v_fma_f32 v72, v72, s8, -v140
	v_fma_f32 v73, v73, s8, -v140
	v_fma_f32 v74, v74, s8, -v140
	s_waitcnt lgkmcnt(0)
	v_mfma_f32_32x32x16_bf16 v[16:31], v[220:223], v[84:87], v[16:31]
	v_fma_f32 v75, v75, s8, -v140
	v_fma_f32 v76, v76, s8, -v140
	v_fma_f32 v77, v77, s8, -v140
	v_fma_f32 v78, v78, s8, -v140
	v_fma_f32 v79, v79, s8, -v140
	v_exp_f32_e32 v72, v72
	v_exp_f32_e32 v73, v73
	v_exp_f32_e32 v74, v74
	v_exp_f32_e32 v75, v75
	v_exp_f32_e32 v76, v76
	v_exp_f32_e32 v77, v77
	v_exp_f32_e32 v78, v78
	v_mfma_f32_32x32x16_bf16 v[0:15], v[224:227], v[84:87], v[0:15]
	v_exp_f32_e32 v79, v79
	v_add_f32_e32 v148, v72, v148
	v_add_f32_e32 v149, v73, v149
	v_add_f32_e32 v148, v74, v148
	v_add_f32_e32 v149, v75, v149
	v_add_f32_e32 v148, v76, v148
	v_add_f32_e32 v149, v77, v149
	v_add_f32_e32 v148, v78, v148
	v_add_f32_e32 v149, v79, v149
	v_cvt_pk_bf16_f32 v64, v72, v73
	v_cvt_pk_bf16_f32 v65, v74, v75
	v_cvt_pk_bf16_f32 v66, v76, v77
	v_cvt_pk_bf16_f32 v67, v78, v79
	v_add_f32_e32 v151, v148, v149
	v_add_f32_e32 v152, v200, v151
	v_mfma_f32_32x32x16_bf16 v[16:31], v[228:231], v[64:67], v[16:31]
	v_max3_f32 v150, v48, s5, v49
	v_max3_f32 v150, v150, v50, v51
	v_max3_f32 v150, v150, v52, v53
	v_max3_f32 v150, v150, v54, v55
	v_max3_f32 v150, v150, v56, v57
	v_max3_f32 v150, v150, v58, v59
	v_max3_f32 v150, v150, v60, v61
	v_max3_f32 v150, v150, v62, v63
	v_mfma_f32_32x32x16_bf16 v[0:15], v[232:235], v[64:67], v[0:15]
	v_max3_f32 v150, v150, v32, v33
	v_max3_f32 v150, v150, v34, v35
	v_max3_f32 v150, v150, v36, v37
	v_max3_f32 v150, v150, v38, v39
	v_max3_f32 v150, v150, v40, v41
	v_max3_f32 v150, v150, v42, v43
	v_max3_f32 v150, v150, v44, v45
	v_max3_f32 v150, v150, v46, v47
	v_mov_b32_e32 v151, v150
	s_nop 1
	v_permlane32_swap_b32_e32 v151, v150
	ds_read2_b64 v[204:207], v238 offset0:64 offset1:66
	ds_read2_b64 v[208:211], v239 offset0:96 offset1:98
	ds_read2_b64 v[212:215], v238 offset0:68 offset1:70
	ds_read2_b64 v[216:219], v239 offset0:100 offset1:102
	ds_read2_b64 v[220:223], v238 offset0:72 offset1:74
	ds_read2_b64 v[224:227], v239 offset0:104 offset1:106
	ds_read2_b64 v[228:231], v238 offset0:76 offset1:78
	ds_read2_b64 v[232:235], v239 offset0:108 offset1:110
	s_waitcnt lgkmcnt(8)
	v_max_f32_e32 v151, v151, v151
	v_max_f32_e32 v150, v150, v151
	v_mul_f32_e32 v150, 0x3e8293ee, v150
	v_cmp_gt_f32_e32 vcc, v150, v146
	s_cbranch_vccz .Laa_nrb
	v_max_f32_e32 v150, v150, v150
	v_max_f32_e32 v151, v140, v140
	v_max_f32_e32 v150, v151, v150
	v_sub_f32_e32 v151, v140, v150
	v_exp_f32_e32 v154, v151
	v_mov_b32_e32 v140, v150
	v_pk_mul_f32 v[16:17], v[16:17], v[154:155] op_sel_hi:[1,0]
	v_pk_mul_f32 v[18:19], v[18:19], v[154:155] op_sel_hi:[1,0]
	v_pk_mul_f32 v[20:21], v[20:21], v[154:155] op_sel_hi:[1,0]
	v_pk_mul_f32 v[22:23], v[22:23], v[154:155] op_sel_hi:[1,0]
	v_pk_mul_f32 v[24:25], v[24:25], v[154:155] op_sel_hi:[1,0]
	v_pk_mul_f32 v[26:27], v[26:27], v[154:155] op_sel_hi:[1,0]
	v_pk_mul_f32 v[28:29], v[28:29], v[154:155] op_sel_hi:[1,0]
	v_pk_mul_f32 v[30:31], v[30:31], v[154:155] op_sel_hi:[1,0]
	v_pk_mul_f32 v[0:1], v[0:1], v[154:155] op_sel_hi:[1,0]
	v_pk_mul_f32 v[2:3], v[2:3], v[154:155] op_sel_hi:[1,0]
	v_pk_mul_f32 v[4:5], v[4:5], v[154:155] op_sel_hi:[1,0]
	v_pk_mul_f32 v[6:7], v[6:7], v[154:155] op_sel_hi:[1,0]
	v_pk_mul_f32 v[8:9], v[8:9], v[154:155] op_sel_hi:[1,0]
	v_pk_mul_f32 v[10:11], v[10:11], v[154:155] op_sel_hi:[1,0]
	v_pk_mul_f32 v[12:13], v[12:13], v[154:155] op_sel_hi:[1,0]
	v_pk_mul_f32 v[14:15], v[14:15], v[154:155] op_sel_hi:[1,0]
	v_mul_f32_e32 v152, v152, v154

; template <int MODE>
; DI void attn_mfma(const Params& p, int l, int b, int hd, int qb, unsigned char* smem) {
;     ...
;     float mx = -1e30f;
; #pragma unroll
;     for (int mt = 0; mt < 2; ++mt)
; #pragma unroll
;       for (int i = 0; i < 16; ++i) mx = fmaxf(mx, S[mt][i]);
;     mx = fmaxf(mx, __shfl_xor(mx, 32));
;     const float zmx = mx * cexp;
;     if (__any(zmx > mrun + 8.f)) {
;       const float mnew = fmaxf(mrun, zmx);
;       const float alpha = __builtin_amdgcn_exp2f(mrun - mnew);
;       mrun = mnew;
;       lsum *= alpha;
;       const f32x2 al2 = {alpha, alpha};
; #pragma unroll
;       for (int vt = 0; vt < 2; ++vt)
; #pragma unroll
;         for (int i = 0; i < 8; ++i) {
;           f32x2 o = {O[vt][2 * i], O[vt][2 * i + 1]};
;           o = o * al2;
;           O[vt][2 * i] = o.x; O[vt][2 * i + 1] = o.y;
;         }
;     }
.Lcc_qkdone:
	ds_read2_b64 v[220:223], v213 offset1:2
	ds_read2_b64 v[224:227], v216 offset0:32 offset1:34
	ds_read2_b64 v[228:231], v213 offset0:4 offset1:6
	ds_read2_b64 v[232:235], v216 offset0:36 offset1:38
	ds_read2_b64 v[236:239], v213 offset0:8 offset1:10
	ds_read2_b64 v[240:243], v216 offset0:40 offset1:42
	ds_read2_b64 v[244:247], v213 offset0:12 offset1:14
	ds_read2_b64 v[248:251], v216 offset0:44 offset1:46
	v_max3_f32 v204, v80, s2, v81
	v_max3_f32 v204, v204, v82, v83
	v_max3_f32 v204, v204, v84, v85
	v_max3_f32 v204, v204, v86, v87
	v_max3_f32 v204, v204, v88, v89
	v_max3_f32 v204, v204, v90, v91
	v_max3_f32 v204, v204, v92, v93
	v_max3_f32 v204, v204, v94, v95
	v_max3_f32 v204, v204, v64, v65
	v_max3_f32 v204, v204, v66, v67
	v_max3_f32 v204, v204, v68, v69
	v_max3_f32 v204, v204, v70, v71
	v_max3_f32 v204, v204, v72, v73
	v_max3_f32 v204, v204, v74, v75
	v_max3_f32 v204, v204, v76, v77
	v_max3_f32 v204, v204, v78, v79
	v_mov_b32_e32 v205, v204
	s_nop 1
	v_permlane32_swap_b32_e32 v205, v204
	s_waitcnt lgkmcnt(0)
	v_max_f32_e32 v205, v205, v205
	v_max_f32_e32 v204, v204, v205
	v_mul_f32_e32 v204, 0x3e38aa3b, v204
	v_add_f32_e32 v206, 0x41000000, v166
	v_cmp_gt_f32_e32 vcc, v204, v206
	s_cbranch_vccz .Lcc_nra
	v_max_f32_e32 v204, v204, v204
	v_max_f32_e32 v205, v166, v166
	v_max_f32_e32 v204, v205, v204
	v_sub_f32_e32 v166, v166, v204
	v_exp_f32_e32 v166, v166
	s_nop 0
	v_pk_mul_f32 v[18:19], v[18:19], v[166:167] op_sel_hi:[1,0]
	v_pk_mul_f32 v[20:21], v[20:21], v[166:167] op_sel_hi:[1,0]
	v_pk_mul_f32 v[22:23], v[22:23], v[166:167] op_sel_hi:[1,0]
	v_pk_mul_f32 v[24:25], v[24:25], v[166:167] op_sel_hi:[1,0]
	v_pk_mul_f32 v[26:27], v[26:27], v[166:167] op_sel_hi:[1,0]
	v_pk_mul_f32 v[28:29], v[28:29], v[166:167] op_sel_hi:[1,0]
	v_pk_mul_f32 v[16:17], v[16:17], v[166:167] op_sel_hi:[1,0]
	v_pk_mul_f32 v[30:31], v[30:31], v[166:167] op_sel_hi:[1,0]
	v_pk_mul_f32 v[0:1], v[0:1], v[166:167] op_sel_hi:[1,0]
	v_pk_mul_f32 v[2:3], v[2:3], v[166:167] op_sel_hi:[1,0]
	v_pk_mul_f32 v[4:5], v[4:5], v[166:167] op_sel_hi:[1,0]
	v_pk_mul_f32 v[6:7], v[6:7], v[166:167] op_sel_hi:[1,0]
	v_pk_mul_f32 v[8:9], v[8:9], v[166:167] op_sel_hi:[1,0]
	v_pk_mul_f32 v[10:11], v[10:11], v[166:167] op_sel_hi:[1,0]
	v_pk_mul_f32 v[12:13], v[12:13], v[166:167] op_sel_hi:[1,0]
	v_pk_mul_f32 v[14:15], v[14:15], v[166:167] op_sel_hi:[1,0]
	v_mul_f32_e32 v200, v200, v166
	v_mov_b32_e32 v166, v204

; template <int MODE>
; DI void attn_mfma(const Params& p, int l, int b, int hd, int qb, unsigned char* smem) {
;     ...
;     float mx = -1e30f;
; #pragma unroll
;     for (int mt = 0; mt < 2; ++mt)
; #pragma unroll
;       for (int i = 0; i < 16; ++i) mx = fmaxf(mx, S[mt][i]);
;     mx = fmaxf(mx, __shfl_xor(mx, 32));
;     const float zmx = mx * cexp;
;     if (__any(zmx > mrun + 8.f)) {
;       const float mnew = fmaxf(mrun, zmx);
;       const float alpha = __builtin_amdgcn_exp2f(mrun - mnew);
;       mrun = mnew;
;       lsum *= alpha;
;       const f32x2 al2 = {alpha, alpha};
; #pragma unroll
;       for (int vt = 0; vt < 2; ++vt)
; #pragma unroll
;         for (int i = 0; i < 8; ++i) {
;           f32x2 o = {O[vt][2 * i], O[vt][2 * i + 1]};
;           o = o * al2;
;           O[vt][2 * i] = o.x; O[vt][2 * i + 1] = o.y;
;         }
;     }
.Lcc_nomaskB:
	v_max3_f32 v210, v48, s2, v49
	v_max3_f32 v210, v210, v50, v51
	v_max3_f32 v210, v210, v52, v53
	v_max3_f32 v210, v210, v54, v55
	v_max3_f32 v210, v210, v56, v57
	v_max3_f32 v210, v210, v58, v59
	v_max3_f32 v210, v210, v60, v61
	v_max3_f32 v210, v210, v62, v63
	v_mfma_f32_32x32x16_bf16 v[0:15], v[248:251], v[64:67], v[0:15]
	v_max3_f32 v210, v210, v32, v33
	v_max3_f32 v210, v210, v34, v35
	v_max3_f32 v210, v210, v36, v37
	v_max3_f32 v210, v210, v38, v39
	v_max3_f32 v210, v210, v40, v41
	v_max3_f32 v210, v210, v42, v43
	v_max3_f32 v210, v210, v44, v45
	v_max3_f32 v210, v210, v46, v47
	v_mov_b32_e32 v211, v210
	s_nop 1
	v_permlane32_swap_b32_e32 v211, v210
	ds_read2_b64 v[220:223], v217 offset0:64 offset1:66
	ds_read2_b64 v[224:227], v218 offset0:96 offset1:98
	ds_read2_b64 v[228:231], v217 offset0:68 offset1:70
	ds_read2_b64 v[232:235], v218 offset0:100 offset1:102
	ds_read2_b64 v[236:239], v217 offset0:72 offset1:74
	ds_read2_b64 v[240:243], v218 offset0:104 offset1:106
	ds_read2_b64 v[244:247], v217 offset0:76 offset1:78
	ds_read2_b64 v[248:251], v218 offset0:108 offset1:110
	s_waitcnt lgkmcnt(8)
	v_max_f32_e32 v211, v211, v211
	v_max_f32_e32 v210, v210, v211
	v_mul_f32_e32 v210, 0x3e38aa3b, v210
	v_add_f32_e32 v211, 0x41000000, v166
	v_cmp_gt_f32_e32 vcc, v210, v211
	s_cbranch_vccz .Lcc_nrb
	v_max_f32_e32 v210, v210, v210
	v_max_f32_e32 v211, v166, v166
	v_max_f32_e32 v210, v211, v210
	v_sub_f32_e32 v211, v166, v210
	v_exp_f32_e32 v214, v211
	v_mov_b32_e32 v166, v210
	v_pk_mul_f32 v[16:17], v[16:17], v[214:215] op_sel_hi:[1,0]
	v_pk_mul_f32 v[18:19], v[18:19], v[214:215] op_sel_hi:[1,0]
	v_pk_mul_f32 v[20:21], v[20:21], v[214:215] op_sel_hi:[1,0]
	v_pk_mul_f32 v[22:23], v[22:23], v[214:215] op_sel_hi:[1,0]
	v_pk_mul_f32 v[24:25], v[24:25], v[214:215] op_sel_hi:[1,0]
	v_pk_mul_f32 v[26:27], v[26:27], v[214:215] op_sel_hi:[1,0]
	v_pk_mul_f32 v[28:29], v[28:29], v[214:215] op_sel_hi:[1,0]
	v_pk_mul_f32 v[30:31], v[30:31], v[214:215] op_sel_hi:[1,0]
	v_pk_mul_f32 v[0:1], v[0:1], v[214:215] op_sel_hi:[1,0]
	v_pk_mul_f32 v[2:3], v[2:3], v[214:215] op_sel_hi:[1,0]
	v_pk_mul_f32 v[4:5], v[4:5], v[214:215] op_sel_hi:[1,0]
	v_pk_mul_f32 v[6:7], v[6:7], v[214:215] op_sel_hi:[1,0]
	v_pk_mul_f32 v[8:9], v[8:9], v[214:215] op_sel_hi:[1,0]
	v_pk_mul_f32 v[10:11], v[10:11], v[214:215] op_sel_hi:[1,0]
	v_pk_mul_f32 v[12:13], v[12:13], v[214:215] op_sel_hi:[1,0]
	v_pk_mul_f32 v[14:15], v[14:15], v[214:215] op_sel_hi:[1,0]
	v_mul_f32_e32 v212, v212, v214
